# code placement: one s_nop 0 before each hand-written attention loop head so the far loop starts at 0 mod 8 bytes (was 4 mod 8) and the near loop at 0 mod 64
# speedup vs baseline: 1.0042x; 1.0042x over previous
; #define AT_LOADK(t) do { AT_DMA(kg[0] + (size_t)(t) * 65536, ldsl + ((t) & 1) * AT_KS + dw); AT_DMA(kg[1] + (size_t)(t) * 65536, ldsl + ((t) & 1) * AT_KS + dw + 1024); } while (0)
; #define AT_LOADV(t) do { AT_DMA(vg[0] + (t) * 64, ldsl + AT_V0 + ((t) & 1) * AT_KS + dw); AT_DMA(vg[1] + (t) * 64, ldsl + AT_V0 + ((t) & 1) * AT_KS + dw + 1024); } while (0)
; template <bool NEAR>
; DI void attn_qk(f32x16& s0, f32x16& s1, ldsp_t kb, const int* kro, const bf16x8* qf, int dtile, const float* tb2, int hi, int qg, int r32) {
;     ...
;         const int base = dtile * 64 + 8 * hi - (qg & 1) * 32 - r32 + 128;
; #pragma unroll
;         for (int k = 0; k < 16; ++k) { const int i0 = base + (k & 7) + 16 * (k >> 3), i1 = i0 + 32; s0[k] = tb2[i0 < 0 ? 0 : i0]; s1[k] = tb2[i1 < 0 ? 0 : i1]; }
; DI void attn_mfma_phase(PP P, int l, unsigned char* lds, int G, int cid) {
;     ...
;         { const bf16_t* qp = Zq + ((size_t)b * SEQ + qpos) * 1024 + h * 128 + map * 64 + 8 * hi;
; #pragma unroll
;           for (int ks = 0; ks < 4; ++ks) qf[ks] = *(const bf16x8*)(qp + ks * 16); }
;         f32x16 o[4];
; #pragma unroll
;         for (int et = 0; et < 4; ++et)
; #pragma unroll
;             for (int k = 0; k < 16; ++k) o[et][k] = 0.f;
;         float lsum = 0.f;
;         const bf16_t* kg[2]; const bf16_t* vg[2];
; #pragma unroll
;         for (int i2 = 0; i2 < 2; ++i2) { const int blk = wave * 2 + i2;
;             { const int row = blk * 4 + (lane >> 4), c = (lane & 15) ^ (row & 15); kg[i2] = Zk + ((size_t)b * SEQ + row) * 1024 + h * 128 + c * 8; }
;             { const int row = blk * 8 + (lane >> 3), c = (lane & 7) ^ ((row >> 1) & 7); vg[i2] = VT + ((size_t)bh * 128 + row) * SEQ + c * 8; } }
;         const int dw = wave * 2048;
;     ...
;         AT_LOADK(0); AT_LOADV(0); AT_LOADK(1);
;         __syncthreads();
;         f32x16 sc0, sc1, sn0, sn1;
;         attn_qk<true>(sc0, sc1, ldsl, kro, qf, 0 - mychunk, tb2, hi, qg, r32);
.LBB0_211:
	s_or_b64 exec, exec, s[12:13]
	s_lshr_b32 s5, s82, 6
	s_and_b32 s6, s67, -4
	s_and_b32 s5, s5, 3
	s_or_b32 s5, s6, s5
	s_lshl_b32 s4, s67, 20
	s_and_b32 s5, s5, 7
	s_bfe_u32 s6, s82, 0x30003
	s_ashr_i32 s42, s82, 5
	s_and_b32 s4, s4, 0x1800000
	s_lshl_b32 s5, s5, 8
	s_and_b32 s9, s42, -16
	s_and_b32 s10, s82, 0x100
	s_xor_b32 s11, s6, 15
	s_cmp_eq_u32 s10, 0
	s_cselect_b32 s43, s6, s11
	s_or_b32 s6, s43, s9
	s_lshl_b32 s12, s6, 7
	s_waitcnt vmcnt(30)
	v_or_b32_e32 v2, s12, v203
	s_lshl_b32 s8, s8, 9
	s_and_b32 s20, s8, 0x3000
	s_waitcnt vmcnt(29)
	v_ashrrev_i32_e32 v3, 31, v2
	v_lshl_add_u64 v[192:193], v[2:3], 0, s[20:21]
	v_lshlrev_b64 v[2:3], 11, v[192:193]
	v_lshl_add_u64 v[2:3], s[46:47], 0, v[2:3]
	s_lshl_b32 s8, s39, 8
	s_mov_b32 s9, s21
	v_lshl_add_u64 v[2:3], v[2:3], 0, s[8:9]
	v_lshl_add_u64 v[2:3], s[16:17], 1, v[2:3]
	v_lshlrev_b32_e32 v0, 1, v162
	v_lshl_add_u64 v[2:3], v[2:3], 0, v[0:1]
	global_load_dwordx4 v[156:159], v[2:3], off
	global_load_dwordx4 v[152:155], v[2:3], off offset:32
	global_load_dwordx4 v[148:151], v[2:3], off offset:64
	global_load_dwordx4 v[144:147], v[2:3], off offset:96
	s_lshl_b32 s13, s6, 1
	s_or_b32 s10, s13, s60
	s_add_u32 s8, s28, s8
	s_addc_u32 s9, s29, 0
	s_lshl_b32 s84, s7, 7
	s_mov_b32 s85, s21
	s_waitcnt vmcnt(31)
	v_lshl_add_u64 v[4:5], s[84:85], 0, v[174:175]
	v_lshl_add_u64 v[2:3], s[20:21], 0, v[172:173]
	v_lshlrev_b64 v[4:5], 13, v[4:5]
	v_lshlrev_b64 v[2:3], 11, v[2:3]
	v_lshl_add_u64 v[194:195], v[180:181], 0, v[4:5]
	v_lshl_add_u64 v[4:5], s[20:21], 0, v[176:177]
	v_lshl_add_u64 v[2:3], s[8:9], 0, v[2:3]
	v_mov_b32_e32 v189, v1
	v_lshlrev_b64 v[4:5], 11, v[4:5]
	s_mov_b32 m0, s65
	v_lshl_add_u64 v[2:3], v[2:3], 0, v[188:189]
	v_lshl_add_u64 v[4:5], s[8:9], 0, v[4:5]
	v_mov_b32_e32 v191, v1
	v_lshl_add_u64 v[4:5], v[4:5], 0, v[190:191]
	s_waitcnt vmcnt(29)
	v_lshl_add_u64 v[6:7], s[84:85], 0, v[178:179]
	global_load_lds_dwordx4 v[2:3], off
	s_add_i32 m0, s65, 0x400
	v_lshlrev_b64 v[6:7], 13, v[6:7]
	global_load_lds_dwordx4 v[4:5], off
	s_add_i32 m0, s65, 0x10000
	v_lshl_add_u64 v[196:197], v[182:183], 0, v[6:7]
	global_load_lds_dwordx4 v[194:195], off
	s_mov_b32 m0, s73
	v_lshl_add_u64 v[2:3], v[2:3], 0, s[34:35]
	global_load_lds_dwordx4 v[196:197], off
	s_add_i32 m0, s65, 0x4000
	v_lshl_or_b32 v0, s10, 6, v216
	global_load_lds_dwordx4 v[2:3], off
	v_lshl_add_u64 v[4:5], v[4:5], 0, s[34:35]
	s_mov_b32 m0, s80
	v_sub_u32_e32 v0, v162, v0
	global_load_lds_dwordx4 v[4:5], off
	s_waitcnt vmcnt(0)
	s_add_i32 m0, s65, 0x14000
	v_lshl_add_u64 v[6:7], v[194:195], 0, s[22:23]
	global_load_lds_dwordx4 v[6:7], off
	s_add_i32 m0, s65, 0x14400
	v_lshl_add_u64 v[8:9], v[196:197], 0, s[22:23]
	global_load_lds_dwordx4 v[8:9], off
	s_add_i32 m0, s65, 0x8000
	v_lshl_add_u64 v[2:3], v[2:3], 0, s[34:35]
	global_load_lds_dwordx4 v[2:3], off
	s_add_i32 m0, s65, 0x8400
	v_lshl_add_u64 v[4:5], v[4:5], 0, s[34:35]
	global_load_lds_dwordx4 v[4:5], off
	s_add_i32 m0, s65, 0x18000
	v_lshl_add_u64 v[6:7], v[6:7], 0, s[22:23]
	global_load_lds_dwordx4 v[6:7], off
	s_add_i32 m0, s65, 0x18400
	v_lshl_add_u64 v[8:9], v[8:9], 0, s[22:23]
	global_load_lds_dwordx4 v[8:9], off
	s_add_i32 m0, s65, 0xc000
	v_lshl_add_u64 v[2:3], v[2:3], 0, s[34:35]
	global_load_lds_dwordx4 v[2:3], off
	s_add_i32 m0, s65, 0xc400
	v_lshl_add_u64 v[4:5], v[4:5], 0, s[34:35]
	global_load_lds_dwordx4 v[4:5], off
	v_add_u32_e32 v10, 0x80, v0
	v_max_i32_e32 v11, 0, v10
	v_max_i32_e32 v10, 0xffffffe0, v10
	v_add_u32_e32 v12, 0x81, v0
	v_add_u32_e32 v14, 0x82, v0
	v_add_u32_e32 v16, 0x83, v0
	v_add_u32_e32 v191, 0, v171
	v_lshl_add_u32 v11, v11, 2, s61
	v_lshl_add_u32 v10, v10, 2, s61
	v_max_i32_e32 v13, 0, v12
	v_max_i32_e32 v12, 0xffffffe0, v12
	v_max_i32_e32 v15, 0, v14
	v_max_i32_e32 v14, 0xffffffe0, v14
	v_max_i32_e32 v17, 0, v16
	v_max_i32_e32 v16, 0xffffffe0, v16
	s_waitcnt lgkmcnt(0)
	s_barrier
	ds_read_b128 v[2:5], v191
	ds_read_b128 v[6:9], v191 offset:8192
	v_lshl_add_u32 v13, v13, 2, s61
	v_lshl_add_u32 v12, v12, 2, s61
	v_lshl_add_u32 v15, v15, 2, s61
	v_lshl_add_u32 v14, v14, 2, s61
	v_lshl_add_u32 v17, v17, 2, s61
	v_lshl_add_u32 v16, v16, 2, s61
	ds_read_b32 v96, v11
	ds_read_b32 v80, v10 offset:128
	ds_read_b32 v97, v13
	ds_read_b32 v81, v12 offset:128
	ds_read_b32 v98, v15
	ds_read_b32 v82, v14 offset:128
	ds_read_b32 v99, v17
	ds_read_b32 v83, v16 offset:128
	v_add_u32_e32 v10, 0x84, v0
	v_max_i32_e32 v11, 0, v10
	v_max_i32_e32 v10, 0xffffffe0, v10
	v_add_u32_e32 v12, 0x85, v0
	v_add_u32_e32 v14, 0x86, v0
	v_add_u32_e32 v16, 0x87, v0
	v_lshl_add_u32 v11, v11, 2, s61
	v_lshl_add_u32 v10, v10, 2, s61
	v_max_i32_e32 v13, 0, v12
	v_max_i32_e32 v12, 0xffffffe0, v12
	v_max_i32_e32 v15, 0, v14
	v_max_i32_e32 v14, 0xffffffe0, v14
	v_max_i32_e32 v17, 0, v16
	v_max_i32_e32 v16, 0xffffffe0, v16
	v_lshl_add_u32 v13, v13, 2, s61
	v_lshl_add_u32 v12, v12, 2, s61
	v_lshl_add_u32 v15, v15, 2, s61
	v_lshl_add_u32 v14, v14, 2, s61
	v_lshl_add_u32 v17, v17, 2, s61
	v_lshl_add_u32 v16, v16, 2, s61
	ds_read_b32 v100, v11
	ds_read_b32 v84, v10 offset:128
	ds_read_b32 v101, v13
	ds_read_b32 v85, v12 offset:128
	ds_read_b32 v102, v15
	ds_read_b32 v86, v14 offset:128
	ds_read_b32 v103, v17
	ds_read_b32 v87, v16 offset:128
	v_add_u32_e32 v10, 0x90, v0
	v_max_i32_e32 v11, 0, v10
	v_max_i32_e32 v10, 0xffffffe0, v10
	v_add_u32_e32 v12, 0x91, v0
	v_add_u32_e32 v14, 0x92, v0
	v_add_u32_e32 v16, 0x93, v0
	v_lshl_add_u32 v11, v11, 2, s61
	v_lshl_add_u32 v10, v10, 2, s61
	v_max_i32_e32 v13, 0, v12
	v_max_i32_e32 v12, 0xffffffe0, v12
	v_max_i32_e32 v15, 0, v14
	v_max_i32_e32 v14, 0xffffffe0, v14
	v_max_i32_e32 v17, 0, v16
	v_max_i32_e32 v16, 0xffffffe0, v16
	v_lshl_add_u32 v13, v13, 2, s61
	v_lshl_add_u32 v12, v12, 2, s61
	v_lshl_add_u32 v15, v15, 2, s61
	v_lshl_add_u32 v14, v14, 2, s61
	v_lshl_add_u32 v17, v17, 2, s61
	v_lshl_add_u32 v16, v16, 2, s61
	ds_read_b32 v104, v11
	ds_read_b32 v88, v10 offset:128
	ds_read_b32 v105, v13
	ds_read_b32 v89, v12 offset:128
	ds_read_b32 v106, v15
	ds_read_b32 v90, v14 offset:128
	ds_read_b32 v107, v17
	ds_read_b32 v91, v16 offset:128
	v_add_u32_e32 v10, 0x94, v0
	v_max_i32_e32 v11, 0, v10
	v_add_u32_e32 v12, 0x95, v0
	v_add_u32_e32 v14, 0x96, v0
	v_add_u32_e32 v0, 0x97, v0
	v_lshl_add_u32 v11, v11, 2, s61
	v_max_i32_e32 v13, 0, v12
	v_max_i32_e32 v15, 0, v14
	v_max_i32_e32 v16, 0, v0
	v_lshl_add_u32 v13, v13, 2, s61
	v_lshl_add_u32 v15, v15, 2, s61
	v_lshl_add_u32 v16, v16, 2, s61
	ds_read_b32 v108, v11
	ds_read_b32 v109, v13
	ds_read_b32 v110, v15
	ds_read_b32 v111, v16
	v_max_i32_e32 v10, 0xffffffe0, v10
	v_max_i32_e32 v12, 0xffffffe0, v12
	v_lshl_add_u32 v10, v10, 2, s61
	v_lshl_add_u32 v12, v12, 2, s61
	v_max_i32_e32 v14, 0xffffffe0, v14
	v_max_i32_e32 v0, 0xffffffe0, v0
	v_add_u32_e32 v229, 0, v200
	v_lshl_add_u32 v11, v14, 2, s61
	v_lshl_add_u32 v0, v0, 2, s61
	ds_read_b32 v92, v10 offset:128
	s_waitcnt lgkmcnt(1)
; template <bool NEAR>
; DI void attn_qk(f32x16& s0, f32x16& s1, ldsp_t kb, const int* kro, const bf16x8* qf, int dtile, const float* tb2, int hi, int qg, int r32) {
;     ...
;     for (int ks = 0; ks < 4; ++ks) { a[2 * ks] = *(const __attribute__((address_space(3))) bf16x8*)(kb + kro[ks]); a[2 * ks + 1] = *(const __attribute__((address_space(3))) bf16x8*)(kb + kro[ks] + 8192); }
;     if (!NEAR) {
;         const float c0 = tb2[0];
; #pragma unroll
;         for (int k = 0; k < 16; ++k) { s0[k] = c0; s1[k] = c0; }
;     } else {
;         const int base = dtile * 64 + 8 * hi - (qg & 1) * 32 - r32 + 128;
; #pragma unroll
;         for (int k = 0; k < 16; ++k) { const int i0 = base + (k & 7) + 16 * (k >> 3), i1 = i0 + 32; s0[k] = tb2[i0 < 0 ? 0 : i0]; s1[k] = tb2[i1 < 0 ? 0 : i1]; }
;     }
; #pragma unroll
;     for (int ks = 0; ks < 4; ++ks) { s0 = MFMA32(a[2 * ks], qf[ks], s0); s1 = MFMA32(a[2 * ks + 1], qf[ks], s1); }
; }
; DI void attn_pv(f32x16& s0, f32x16& s1, ldsp_t vb, const int* vro, f32x16* o, float& lsum) {
; #pragma unroll
;     for (int k = 0; k < 16; ++k) { s0[k] = __builtin_amdgcn_exp2f(s0[k]); s1[k] = __builtin_amdgcn_exp2f(s1[k]); }
;     float ps = 0.f;
; #pragma unroll
;     for (int k = 0; k < 16; ++k) ps += s0[k] + s1[k];
;     lsum += ps;
;     bf16x8 pk[4]; pk[0] = pack8(s0, 0); pk[1] = pack8(s0, 1); pk[2] = pack8(s1, 0); pk[3] = pack8(s1, 1);
; DI void attn_mfma_phase(PP P, int l, unsigned char* lds, int G, int cid) {
;     ...
;         f32x16 o[4];
; #pragma unroll
;         for (int et = 0; et < 4; ++et)
; #pragma unroll
;             for (int k = 0; k < 16; ++k) o[et][k] = 0.f;
;         float lsum = 0.f;
;         const bf16_t* kg[2]; const bf16_t* vg[2];
; #pragma unroll
;         for (int i2 = 0; i2 < 2; ++i2) { const int blk = wave * 2 + i2;
;             { const int row = blk * 4 + (lane >> 4), c = (lane & 15) ^ (row & 15); kg[i2] = Zk + ((size_t)b * SEQ + row) * 1024 + h * 128 + c * 8; }
;             { const int row = blk * 8 + (lane >> 3), c = (lane & 7) ^ ((row >> 1) & 7); vg[i2] = VT + ((size_t)bh * 128 + row) * SEQ + c * 8; } }
;         const int dw = wave * 2048;
;     ...
;         AT_LOADK(0); AT_LOADV(0); AT_LOADK(1);
;         __syncthreads();
;         f32x16 sc0, sc1, sn0, sn1;
;         attn_qk<true>(sc0, sc1, ldsl, kro, qf, 0 - mychunk, tb2, hi, qg, r32);
;         const int nfar = 2 * j - 3;
;         int kt = 0;
	v_mfma_f32_32x32x16_bf16 v[96:111], v[2:5], v[156:159], v[96:111]
	ds_read_b32 v93, v12 offset:128
	ds_read_b32 v94, v11 offset:128
	ds_read_b32 v95, v0 offset:128
	ds_read_b128 v[2:5], v229
	v_add_u32_e32 v230, 0, v201
	v_add_u32_e32 v231, 0, v202
	s_mov_b32 s38, 0
	s_cmp_lt_i32 s6, 2
	s_waitcnt lgkmcnt(0)
	v_mfma_f32_32x32x16_bf16 v[96:111], v[2:5], v[152:155], v[96:111]
	ds_read_b128 v[2:5], v229 offset:8192
	v_mfma_f32_32x32x16_bf16 v[80:95], v[6:9], v[156:159], v[80:95]
	s_waitcnt lgkmcnt(0)
	v_mfma_f32_32x32x16_bf16 v[80:95], v[2:5], v[152:155], v[80:95]
	ds_read_b128 v[2:5], v230
	s_waitcnt lgkmcnt(0)
	v_mfma_f32_32x32x16_bf16 v[96:111], v[2:5], v[148:151], v[96:111]
	ds_read_b128 v[2:5], v230 offset:8192
	s_waitcnt lgkmcnt(0)
	v_mfma_f32_32x32x16_bf16 v[80:95], v[2:5], v[148:151], v[80:95]
	ds_read_b128 v[2:5], v231
	s_waitcnt lgkmcnt(0)
	v_mfma_f32_32x32x16_bf16 v[96:111], v[2:5], v[144:147], v[96:111]
	ds_read_b128 v[2:5], v231 offset:8192
	s_waitcnt lgkmcnt(0)
	v_mfma_f32_32x32x16_bf16 v[80:95], v[2:5], v[144:147], v[80:95]
	s_cbranch_scc1 .LBB0_215
	s_add_u32 s6, s4, s5
	s_addc_u32 s7, 0, 0
	v_lshl_add_u64 v[10:11], v[184:185], 0, s[6:7]
	v_lshl_add_u64 v[12:13], v[186:187], 0, s[6:7]
	s_lshl_b32 s6, s42, 1
	s_andn2_b32 s6, s6, 31
	s_lshl_b32 s7, s43, 1
	s_or_b32 s6, s6, s7
	s_add_i32 s6, s6, -3
	s_max_i32 s38, s6, 1
	s_sub_i32 s7, 0, s38
	v_mov_b32_e32 v189, 0
	s_movk_i32 s6, 0x4000
	s_mov_b32 s20, 0xc0
	v_mov_b32_e32 v232, s7
	v_mov_b32_e32 v64, 0
	v_mov_b32_e32 v65, v189
	v_mov_b32_e32 v66, v189
	v_mov_b32_e32 v67, v189
	v_mov_b32_e32 v68, v189
	v_mov_b32_e32 v69, v189
	v_mov_b32_e32 v70, v189
	v_mov_b32_e32 v71, v189
	v_mov_b32_e32 v72, v189
	v_mov_b32_e32 v73, v189
	v_mov_b32_e32 v74, v189
	v_mov_b32_e32 v75, v189
	v_mov_b32_e32 v76, v189
	v_mov_b32_e32 v77, v189
	v_mov_b32_e32 v78, v189
	v_mov_b32_e32 v79, v189
	v_mov_b32_e32 v48, 0
	v_mov_b32_e32 v49, v189
	v_mov_b32_e32 v50, v189
	v_mov_b32_e32 v51, v189
	v_mov_b32_e32 v52, v189
	v_mov_b32_e32 v53, v189
	v_mov_b32_e32 v54, v189
	v_mov_b32_e32 v55, v189
	v_mov_b32_e32 v56, v189
	v_mov_b32_e32 v57, v189
	v_mov_b32_e32 v58, v189
	v_mov_b32_e32 v59, v189
	v_mov_b32_e32 v60, v189
	v_mov_b32_e32 v61, v189
	v_mov_b32_e32 v62, v189
	v_mov_b32_e32 v63, v189
	v_mov_b32_e32 v32, 0
	v_mov_b32_e32 v33, v189
	v_mov_b32_e32 v34, v189
	v_mov_b32_e32 v35, v189
	v_mov_b32_e32 v36, v189
	v_mov_b32_e32 v37, v189
	v_mov_b32_e32 v38, v189
	v_mov_b32_e32 v39, v189
	v_mov_b32_e32 v40, v189
	v_mov_b32_e32 v41, v189
	v_mov_b32_e32 v42, v189
	v_mov_b32_e32 v43, v189
	v_mov_b32_e32 v44, v189
	v_mov_b32_e32 v45, v189
	v_mov_b32_e32 v46, v189
	v_mov_b32_e32 v47, v189
	v_mov_b32_e32 v16, 0
	v_mov_b32_e32 v17, v189
	v_mov_b32_e32 v18, v189
	v_mov_b32_e32 v19, v189
	v_mov_b32_e32 v20, v189
	v_mov_b32_e32 v21, v189
	v_mov_b32_e32 v22, v189
	v_mov_b32_e32 v23, v189
	v_mov_b32_e32 v24, v189
	v_mov_b32_e32 v25, v189
	v_mov_b32_e32 v26, v189
	v_mov_b32_e32 v27, v189
	v_mov_b32_e32 v28, v189
	v_mov_b32_e32 v29, v189
	v_mov_b32_e32 v30, v189
	v_mov_b32_e32 v31, v189
	v_mov_b32_e32 v0, s61
	ds_read_b32 v112, v0
	v_exp_f32_e32 v14, v96
	v_exp_f32_e32 v15, v97
	v_exp_f32_e32 v168, v98
	v_exp_f32_e32 v169, v99
	v_exp_f32_e32 v198, v100
	v_exp_f32_e32 v199, v101
	v_exp_f32_e32 v238, v102
	v_exp_f32_e32 v239, v103
	v_cvt_pk_bf16_f32 v128, v14, v15
	v_cvt_pk_bf16_f32 v129, v168, v169
	v_add_f32_e32 v14, v14, v15
	v_add_f32_e32 v168, v168, v169
	v_cvt_pk_bf16_f32 v130, v198, v199
	v_cvt_pk_bf16_f32 v131, v238, v239
	v_add_f32_e32 v198, v198, v199
	v_add_f32_e32 v238, v238, v239
	v_add_f32_e32 v14, v14, v168
	v_add_f32_e32 v198, v198, v238
	v_add_f32_e32 v235, v14, v198
	s_waitcnt lgkmcnt(0)
	v_mov_b32_e32 v113, v112
	v_mov_b32_e32 v114, v112
	v_mov_b32_e32 v115, v112
	v_mov_b32_e32 v116, v112
	v_mov_b32_e32 v117, v112
	v_mov_b32_e32 v118, v112
	v_mov_b32_e32 v119, v112
	v_mov_b32_e32 v120, v112
	v_mov_b32_e32 v121, v112
	v_mov_b32_e32 v122, v112
	v_mov_b32_e32 v123, v112
	v_mov_b32_e32 v124, v112
	v_mov_b32_e32 v125, v112
	v_mov_b32_e32 v126, v112
	v_mov_b32_e32 v127, v112
	s_nop 0

; #define AT_LOADK(t) do { AT_DMA(kg[0] + (size_t)(t) * 65536, ldsl + ((t) & 1) * AT_KS + dw); AT_DMA(kg[1] + (size_t)(t) * 65536, ldsl + ((t) & 1) * AT_KS + dw + 1024); } while (0)
; #define AT_LOADV(t) do { AT_DMA(vg[0] + (t) * 64, ldsl + AT_V0 + ((t) & 1) * AT_KS + dw); AT_DMA(vg[1] + (t) * 64, ldsl + AT_V0 + ((t) & 1) * AT_KS + dw + 1024); } while (0)
; DI void attn_pv(f32x16& s0, f32x16& s1, ldsp_t vb, const int* vro, f32x16* o, float& lsum) {
; #pragma unroll
;     for (int k = 0; k < 16; ++k) { s0[k] = __builtin_amdgcn_exp2f(s0[k]); s1[k] = __builtin_amdgcn_exp2f(s1[k]); }
;     float ps = 0.f;
; #pragma unroll
;     for (int k = 0; k < 16; ++k) ps += s0[k] + s1[k];
;     lsum += ps;
;     bf16x8 pk[4]; pk[0] = pack8(s0, 0); pk[1] = pack8(s0, 1); pk[2] = pack8(s1, 0); pk[3] = pack8(s1, 1);
; DI void attn_mfma_phase(PP P, int l, unsigned char* lds, int G, int cid) {
;     ...
;         for (; kt < 2 * j; ++kt) {
;             AT_LOADK(kt + 2); AT_LOADV(kt + 1);
;             attn_qk<true>(sn0, sn1, ldsl + ((kt + 1) & 1) * AT_KS, kro, qf, kt + 1 - mychunk, tb2, hi, qg, r32);
;             attn_pv(sc0, sc1, ldsl + (kt & 1) * AT_KS, vro, o, lsum);
.LBB0_216:
	s_lshl_b32 s6, s43, 7
	v_subrev_u32_e32 v0, s6, v228
	s_lshl_b32 s6, s42, 7
	s_and_b32 s6, s6, 0xfffff800
	s_mov_b32 s39, s21
	s_lshl_b32 s84, s38, 6
	v_subrev_u32_e32 v232, s6, v0
	s_lshl_b32 s42, s38, 14
	s_lshl_b64 s[6:7], s[38:39], 17
	s_add_u32 s4, s4, s6
	s_addc_u32 s6, 0, s7
	s_add_u32 s4, s4, s5
	s_addc_u32 s5, s6, 0
	v_lshl_add_u64 v[10:11], v[184:185], 0, s[4:5]
	v_lshl_add_u64 v[12:13], v[186:187], 0, s[4:5]
	s_mov_b32 s4, 0xc0
	v_exp_f32_e32 v14, v96
	v_exp_f32_e32 v15, v97
	v_exp_f32_e32 v168, v98
	v_exp_f32_e32 v169, v99
	v_exp_f32_e32 v198, v100
	v_exp_f32_e32 v199, v101
	v_exp_f32_e32 v238, v102
	v_exp_f32_e32 v239, v103
	v_cvt_pk_bf16_f32 v128, v14, v15
	v_cvt_pk_bf16_f32 v129, v168, v169
	v_add_f32_e32 v14, v14, v15
	v_add_f32_e32 v168, v168, v169
	v_cvt_pk_bf16_f32 v130, v198, v199
	v_cvt_pk_bf16_f32 v131, v238, v239
	v_add_f32_e32 v198, v198, v199
	v_add_f32_e32 v238, v238, v239
	v_add_f32_e32 v14, v14, v168
	v_add_f32_e32 v198, v198, v238
	v_add_f32_e32 v235, v14, v198
	s_nop 0
